# shadow f32 GEMM (K=1024): LDS-fill loads all issued up front instead of 8 serialized rounds
# speedup vs baseline: 1.0005x; 1.0005x over previous
; template <int M> DEVI float shx(float v) { return __int_as_float(__builtin_amdgcn_ds_swizzle(__float_as_int(v), (M << 10) | 0x1f)); }
; DEVI void sk_gemm(const float* __restrict__ A, int lda, int K, const float* __restrict__ W, int N, const float* __restrict__ gain,
;                   bool use_rs, float* __restrict__ out, int ldo, int mode, unsigned char* lds, int wv, int bid, int nblk) {
;     ...
;   for (int grp = bid; grp < ngrp; grp += nblk) {
;     const int n = grp * 16 + c16; const int nl = n < N ? n : N - 1;
;     float acc[16];
; #pragma unroll
;     for (int b = 0; b < 16; ++b) acc[b] = 0.f;
; #pragma unroll 1
;     for (int k0 = 0; k0 < K; k0 += 1024) {
;       const int kc = (K - k0) < 1024 ? (K - k0) : 1024;
;       __syncthreads();
;       {
;         const int b = tid >> 5, j = tid & 31; float ss = 0.f;
; #pragma unroll 8
;         for (int k = j; k < kc; k += 32) { const float v = A[(size_t)b * lda + k0 + k]; ss += v * v; As[b * 1024 + k] = v * gain[k0 + k]; }
;         if (use_rs) { ss += shx<16>(ss); ss += shx<8>(ss); ss += shx<4>(ss); ss += shx<2>(ss); ss += shx<1>(ss); if (j == 0) rsS[b] = rsqrtf(ss / (float)K + 1e-6f); }
;       }
;       __syncthreads();
.LBB0_305:
	v_ashrrev_i32_e32 v145, 31, v144
	s_mov_b64 s[4:5], 0x3ff
	v_cmp_gt_i64_e64 s[4:5], s[4:5], v[144:145]
	s_barrier
	s_nop 0
	v_cndmask_b32_e64 v1, 0, v145, s[4:5]
	v_cndmask_b32_e64 v0, v226, v144, s[4:5]
	v_lshl_add_u64 v[146:147], v[0:1], 2, v[142:143]
	global_load_dword v6, v[6:7], off
	global_load_dword v8, v[8:9], off
	global_load_dword v10, v[10:11], off
	global_load_dword v12, v[12:13], off
	global_load_dword v14, v[14:15], off
	global_load_dword v16, v[16:17], off
	global_load_dword v18, v[18:19], off
	global_load_dword v20, v[20:21], off
	global_load_dword v22, v[22:23], off
	global_load_dword v24, v[24:25], off
	global_load_dword v26, v[26:27], off
	global_load_dword v28, v[28:29], off
	global_load_dword v30, v[30:31], off
	global_load_dword v34, v[34:35], off
	global_load_dword v36, v[36:37], off
	global_load_dword v38, v[38:39], off
	global_load_dword v40, v[40:41], off
	global_load_dword v42, v[42:43], off
	global_load_dword v44, v[44:45], off
	global_load_dword v46, v[46:47], off
	global_load_dword v48, v[48:49], off
	global_load_dword v50, v[50:51], off
	global_load_dword v52, v[52:53], off
	global_load_dword v54, v[54:55], off
	global_load_dword v56, v[56:57], off
	global_load_dword v58, v[58:59], off
	global_load_dword v60, v[60:61], off
	global_load_dword v62, v[62:63], off
	global_load_dword v64, v[64:65], off
	global_load_dword v66, v[66:67], off
	global_load_dword v68, v[68:69], off
	global_load_dword v70, v[70:71], off
	global_load_dword v72, v[72:73], off
	global_load_dword v74, v[74:75], off
	global_load_dword v80, v[80:81], off
	global_load_dword v84, v[84:85], off
	global_load_dword v76, v[76:77], off
	global_load_dword v78, v[78:79], off
	global_load_dword v82, v[82:83], off
	global_load_dword v86, v[86:87], off
	global_load_dword v88, v[88:89], off
	global_load_dword v92, v[92:93], off
	global_load_dword v96, v[96:97], off
	global_load_dword v100, v[100:101], off
	global_load_dword v90, v[90:91], off
	global_load_dword v94, v[94:95], off
	global_load_dword v98, v[98:99], off
	global_load_dword v102, v[102:103], off
	global_load_dword v104, v[104:105], off
	global_load_dword v108, v[108:109], off
	global_load_dword v112, v[112:113], off
	global_load_dword v116, v[116:117], off
	global_load_dword v106, v[106:107], off
	global_load_dword v110, v[110:111], off
	global_load_dword v114, v[114:115], off
	global_load_dword v118, v[118:119], off
	global_load_dword v120, v[120:121], off
	global_load_dword v122, v[122:123], off
	global_load_dword v124, v[124:125], off
	global_load_dword v126, v[126:127], off
	global_load_dword v128, v[128:129], off
	global_load_dword v136, v[136:137], off
	global_load_dword v138, v[138:139], off
	global_load_dword v140, v[140:141], off
	v_add_u32_e32 v32, 0x400, v171
	v_mov_b32_e32 v162, 0
	s_mov_b32 s3, -4
	v_mov_b32_e32 v145, v173
	v_mov_b32_e32 v163, v162
	v_mov_b32_e32 v148, v162
	v_mov_b32_e32 v149, v162
	v_mov_b32_e32 v150, v162
	v_mov_b32_e32 v151, v162
	v_mov_b32_e32 v152, v162
	v_mov_b32_e32 v153, v162
	v_mov_b32_e32 v154, v162
	v_mov_b32_e32 v155, v162
	v_mov_b32_e32 v156, v162
	v_mov_b32_e32 v157, v162
	v_mov_b32_e32 v158, v162
	v_mov_b32_e32 v159, v162
	v_mov_b32_e32 v160, v162
	v_mov_b32_e32 v161, v162
	s_mov_b64 s[10:11], 0x8000
	s_waitcnt vmcnt(56)
	v_mul_f32_e32 v6, v6, v14
	v_mul_f32_e32 v8, v8, v16
	v_mul_f32_e32 v10, v10, v18
	v_mul_f32_e32 v12, v12, v20
	ds_write2_b32 v171, v6, v8 offset1:32
	ds_write2_b32 v171, v10, v12 offset0:64 offset1:96
	s_waitcnt vmcnt(48)
	v_mul_f32_e32 v22, v22, v30
	v_mul_f32_e32 v24, v24, v34
	v_mul_f32_e32 v26, v26, v36
	v_mul_f32_e32 v28, v28, v38
	ds_write2_b32 v171, v22, v24 offset0:128 offset1:160
	ds_write2_b32 v171, v26, v28 offset0:192 offset1:224
	s_waitcnt vmcnt(40)
	v_mul_f32_e32 v40, v40, v48
	v_mul_f32_e32 v42, v42, v50
	v_mul_f32_e32 v44, v44, v52
	v_mul_f32_e32 v46, v46, v54
	ds_write2_b32 v32, v40, v42 offset1:32
	ds_write2_b32 v32, v44, v46 offset0:64 offset1:96
	s_waitcnt vmcnt(32)
	v_mul_f32_e32 v56, v56, v64
	v_mul_f32_e32 v58, v58, v66
	v_mul_f32_e32 v60, v60, v68
	v_mul_f32_e32 v62, v62, v70
	ds_write2_b32 v32, v56, v58 offset0:128 offset1:160
	ds_write2_b32 v32, v60, v62 offset0:192 offset1:224
	v_add_u32_e32 v32, 0x800, v171
	s_waitcnt vmcnt(24)
	v_mul_f32_e32 v72, v72, v76
	v_mul_f32_e32 v74, v74, v78
	v_mul_f32_e32 v80, v80, v82
	v_mul_f32_e32 v84, v84, v86
	ds_write2_b32 v32, v72, v74 offset1:32
	ds_write2_b32 v32, v80, v84 offset0:64 offset1:96
	s_waitcnt vmcnt(16)
	v_mul_f32_e32 v88, v88, v90
	v_mul_f32_e32 v92, v92, v94
	v_mul_f32_e32 v96, v96, v98
	v_mul_f32_e32 v100, v100, v102
	ds_write2_b32 v32, v88, v92 offset0:128 offset1:160
	ds_write2_b32 v32, v96, v100 offset0:192 offset1:224
	v_add_u32_e32 v32, 0xc00, v171
	s_waitcnt vmcnt(8)
	v_mul_f32_e32 v104, v104, v106
	v_mul_f32_e32 v108, v108, v110
	v_mul_f32_e32 v112, v112, v114
	v_mul_f32_e32 v116, v116, v118
	ds_write2_b32 v32, v104, v108 offset1:32
	ds_write2_b32 v32, v112, v116 offset0:64 offset1:96
	s_waitcnt vmcnt(0)
	v_mul_f32_e32 v120, v120, v128
	v_mul_f32_e32 v122, v122, v136
	v_mul_f32_e32 v124, v124, v138
	v_mul_f32_e32 v126, v126, v140
	ds_write2_b32 v32, v120, v122 offset0:128 offset1:160
	ds_write2_b32 v32, v124, v126 offset0:192 offset1:224
	s_waitcnt lgkmcnt(0)
	s_barrier

; template <int M> DEVI float shx(float v) { return __int_as_float(__builtin_amdgcn_ds_swizzle(__float_as_int(v), (M << 10) | 0x1f)); }
; DEVI void sk_gemm(const float* __restrict__ A, int lda, int K, const float* __restrict__ W, int N, const float* __restrict__ gain,
;                   bool use_rs, float* __restrict__ out, int ldo, int mode, unsigned char* lds, int wv, int bid, int nblk) {
;     ...
;   for (int grp = bid; grp < ngrp; grp += nblk) {
;     const int n = grp * 16 + c16; const int nl = n < N ? n : N - 1;
;     float acc[16];
; #pragma unroll
;     for (int b = 0; b < 16; ++b) acc[b] = 0.f;
; #pragma unroll 1
;     for (int k0 = 0; k0 < K; k0 += 1024) {
;       const int kc = (K - k0) < 1024 ? (K - k0) : 1024;
;       __syncthreads();
;       {
;         const int b = tid >> 5, j = tid & 31; float ss = 0.f;
; #pragma unroll 8
;         for (int k = j; k < kc; k += 32) { const float v = A[(size_t)b * lda + k0 + k]; ss += v * v; As[b * 1024 + k] = v * gain[k0 + k]; }
;         if (use_rs) { ss += shx<16>(ss); ss += shx<8>(ss); ss += shx<4>(ss); ss += shx<2>(ss); ss += shx<1>(ss); if (j == 0) rsS[b] = rsqrtf(ss / (float)K + 1e-6f); }
;       }
;       __syncthreads();
.LBB0_679:
	v_ashrrev_i32_e32 v145, 31, v144
	s_mov_b64 s[4:5], 0x3ff
	v_cmp_gt_i64_e64 s[4:5], s[4:5], v[144:145]
	s_barrier
	s_nop 0
	v_cndmask_b32_e64 v1, 0, v145, s[4:5]
	v_cndmask_b32_e64 v0, v226, v144, s[4:5]
	v_lshl_add_u64 v[146:147], v[0:1], 2, v[142:143]
	global_load_dword v6, v[6:7], off
	global_load_dword v8, v[8:9], off
	global_load_dword v10, v[10:11], off
	global_load_dword v12, v[12:13], off
	global_load_dword v14, v[14:15], off
	global_load_dword v16, v[16:17], off
	global_load_dword v18, v[18:19], off
	global_load_dword v20, v[20:21], off
	global_load_dword v22, v[22:23], off
	global_load_dword v24, v[24:25], off
	global_load_dword v26, v[26:27], off
	global_load_dword v28, v[28:29], off
	global_load_dword v30, v[30:31], off
	global_load_dword v34, v[34:35], off
	global_load_dword v36, v[36:37], off
	global_load_dword v38, v[38:39], off
	global_load_dword v40, v[40:41], off
	global_load_dword v42, v[42:43], off
	global_load_dword v44, v[44:45], off
	global_load_dword v46, v[46:47], off
	global_load_dword v48, v[48:49], off
	global_load_dword v50, v[50:51], off
	global_load_dword v52, v[52:53], off
	global_load_dword v54, v[54:55], off
	global_load_dword v56, v[56:57], off
	global_load_dword v58, v[58:59], off
	global_load_dword v60, v[60:61], off
	global_load_dword v62, v[62:63], off
	global_load_dword v64, v[64:65], off
	global_load_dword v66, v[66:67], off
	global_load_dword v68, v[68:69], off
	global_load_dword v70, v[70:71], off
	global_load_dword v72, v[72:73], off
	global_load_dword v74, v[74:75], off
	global_load_dword v76, v[76:77], off
	global_load_dword v78, v[78:79], off
	global_load_dword v80, v[80:81], off
	global_load_dword v82, v[82:83], off
	global_load_dword v84, v[84:85], off
	global_load_dword v86, v[86:87], off
	global_load_dword v88, v[88:89], off
	global_load_dword v90, v[90:91], off
	global_load_dword v92, v[92:93], off
	global_load_dword v94, v[94:95], off
	global_load_dword v96, v[96:97], off
	global_load_dword v98, v[98:99], off
	global_load_dword v100, v[100:101], off
	global_load_dword v102, v[102:103], off
	global_load_dword v104, v[104:105], off
	global_load_dword v106, v[106:107], off
	global_load_dword v108, v[108:109], off
	global_load_dword v110, v[110:111], off
	global_load_dword v112, v[112:113], off
	global_load_dword v114, v[114:115], off
	global_load_dword v116, v[116:117], off
	global_load_dword v118, v[118:119], off
	global_load_dword v120, v[120:121], off
	global_load_dword v122, v[122:123], off
	global_load_dword v124, v[124:125], off
	global_load_dword v126, v[126:127], off
	global_load_dword v128, v[128:129], off
	global_load_dword v136, v[136:137], off
	global_load_dword v138, v[138:139], off
	global_load_dword v140, v[140:141], off
	v_add_u32_e32 v32, 0x400, v171
	v_mov_b32_e32 v162, 0
	s_mov_b32 s3, -4
	v_mov_b32_e32 v145, v172
	v_mov_b32_e32 v163, v162
	v_mov_b32_e32 v148, v162
	v_mov_b32_e32 v149, v162
	v_mov_b32_e32 v150, v162
	v_mov_b32_e32 v151, v162
	v_mov_b32_e32 v152, v162
	v_mov_b32_e32 v153, v162
	v_mov_b32_e32 v154, v162
	v_mov_b32_e32 v155, v162
	v_mov_b32_e32 v156, v162
	v_mov_b32_e32 v157, v162
	v_mov_b32_e32 v158, v162
	v_mov_b32_e32 v159, v162
	v_mov_b32_e32 v160, v162
	v_mov_b32_e32 v161, v162
	s_mov_b64 s[10:11], 0x8000
	s_waitcnt vmcnt(56)
	v_mul_f32_e32 v6, v6, v14
	v_mul_f32_e32 v8, v8, v16
	v_mul_f32_e32 v10, v10, v18
	v_mul_f32_e32 v12, v12, v20
	ds_write2_b32 v171, v6, v8 offset1:32
	ds_write2_b32 v171, v10, v12 offset0:64 offset1:96
	s_waitcnt vmcnt(48)
	v_mul_f32_e32 v22, v22, v30
	v_mul_f32_e32 v24, v24, v34
	v_mul_f32_e32 v26, v26, v36
	v_mul_f32_e32 v28, v28, v38
	ds_write2_b32 v171, v22, v24 offset0:128 offset1:160
	ds_write2_b32 v171, v26, v28 offset0:192 offset1:224
	s_waitcnt vmcnt(40)
	v_mul_f32_e32 v40, v40, v48
	v_mul_f32_e32 v42, v42, v50
	v_mul_f32_e32 v44, v44, v52
	v_mul_f32_e32 v46, v46, v54
	ds_write2_b32 v32, v40, v42 offset1:32
	ds_write2_b32 v32, v44, v46 offset0:64 offset1:96
	s_waitcnt vmcnt(32)
	v_mul_f32_e32 v56, v56, v64
	v_mul_f32_e32 v58, v58, v66
	v_mul_f32_e32 v60, v60, v68
	v_mul_f32_e32 v62, v62, v70
	ds_write2_b32 v32, v56, v58 offset0:128 offset1:160
	ds_write2_b32 v32, v60, v62 offset0:192 offset1:224
	v_add_u32_e32 v32, 0x800, v171
	s_waitcnt vmcnt(24)
	v_mul_f32_e32 v72, v72, v80
	v_mul_f32_e32 v74, v74, v82
	v_mul_f32_e32 v76, v76, v84
	v_mul_f32_e32 v78, v78, v86
	ds_write2_b32 v32, v72, v74 offset1:32
	ds_write2_b32 v32, v76, v78 offset0:64 offset1:96
	s_waitcnt vmcnt(16)
	v_mul_f32_e32 v88, v88, v96
	v_mul_f32_e32 v90, v90, v98
	v_mul_f32_e32 v92, v92, v100
	v_mul_f32_e32 v94, v94, v102
	ds_write2_b32 v32, v88, v90 offset0:128 offset1:160
	ds_write2_b32 v32, v92, v94 offset0:192 offset1:224
	v_add_u32_e32 v32, 0xc00, v171
	s_waitcnt vmcnt(8)
	v_mul_f32_e32 v104, v104, v112
	v_mul_f32_e32 v106, v106, v114
	v_mul_f32_e32 v108, v108, v116
	v_mul_f32_e32 v110, v110, v118
	ds_write2_b32 v32, v104, v106 offset1:32
	ds_write2_b32 v32, v108, v110 offset0:64 offset1:96
	s_waitcnt vmcnt(0)
	v_mul_f32_e32 v120, v120, v128
	v_mul_f32_e32 v122, v122, v136
	v_mul_f32_e32 v124, v124, v138
	v_mul_f32_e32 v126, v126, v140
	ds_write2_b32 v32, v120, v122 offset0:128 offset1:160
	ds_write2_b32 v32, v124, v126 offset0:192 offset1:224
	s_waitcnt lgkmcnt(0)
	s_barrier

; template <int M> DEVI float shx(float v) { return __int_as_float(__builtin_amdgcn_ds_swizzle(__float_as_int(v), (M << 10) | 0x1f)); }
; DEVI void sk_gemm(const float* __restrict__ A, int lda, int K, const float* __restrict__ W, int N, const float* __restrict__ gain,
;                   bool use_rs, float* __restrict__ out, int ldo, int mode, unsigned char* lds, int wv, int bid, int nblk) {
;     ...
;   for (int grp = bid; grp < ngrp; grp += nblk) {
;     const int n = grp * 16 + c16; const int nl = n < N ? n : N - 1;
;     float acc[16];
; #pragma unroll
;     for (int b = 0; b < 16; ++b) acc[b] = 0.f;
; #pragma unroll 1
;     for (int k0 = 0; k0 < K; k0 += 1024) {
;       const int kc = (K - k0) < 1024 ? (K - k0) : 1024;
;       __syncthreads();
;       {
;         const int b = tid >> 5, j = tid & 31; float ss = 0.f;
; #pragma unroll 8
;         for (int k = j; k < kc; k += 32) { const float v = A[(size_t)b * lda + k0 + k]; ss += v * v; As[b * 1024 + k] = v * gain[k0 + k]; }
;         if (use_rs) { ss += shx<16>(ss); ss += shx<8>(ss); ss += shx<4>(ss); ss += shx<2>(ss); ss += shx<1>(ss); if (j == 0) rsS[b] = rsqrtf(ss / (float)K + 1e-6f); }
;       }
;       __syncthreads();
.LBB0_1097:
	v_ashrrev_i32_e32 v145, 31, v144
	s_mov_b64 s[4:5], 0x3ff
	v_cmp_gt_i64_e64 s[4:5], s[4:5], v[144:145]
	s_barrier
	s_nop 0
	v_cndmask_b32_e64 v1, 0, v145, s[4:5]
	v_cndmask_b32_e64 v0, v226, v144, s[4:5]
	v_lshl_add_u64 v[146:147], v[0:1], 2, v[142:143]
	global_load_dword v6, v[6:7], off
	global_load_dword v8, v[8:9], off
	global_load_dword v10, v[10:11], off
	global_load_dword v12, v[12:13], off
	global_load_dword v14, v[14:15], off
	global_load_dword v16, v[16:17], off
	global_load_dword v18, v[18:19], off
	global_load_dword v20, v[20:21], off
	global_load_dword v22, v[22:23], off
	global_load_dword v24, v[24:25], off
	global_load_dword v26, v[26:27], off
	global_load_dword v28, v[28:29], off
	global_load_dword v30, v[30:31], off
	global_load_dword v34, v[34:35], off
	global_load_dword v36, v[36:37], off
	global_load_dword v38, v[38:39], off
	global_load_dword v40, v[40:41], off
	global_load_dword v42, v[42:43], off
	global_load_dword v44, v[44:45], off
	global_load_dword v46, v[46:47], off
	global_load_dword v48, v[48:49], off
	global_load_dword v50, v[50:51], off
	global_load_dword v52, v[52:53], off
	global_load_dword v54, v[54:55], off
	global_load_dword v56, v[56:57], off
	global_load_dword v58, v[58:59], off
	global_load_dword v60, v[60:61], off
	global_load_dword v62, v[62:63], off
	global_load_dword v64, v[64:65], off
	global_load_dword v66, v[66:67], off
	global_load_dword v68, v[68:69], off
	global_load_dword v70, v[70:71], off
	global_load_dword v72, v[72:73], off
	global_load_dword v74, v[74:75], off
	global_load_dword v76, v[76:77], off
	global_load_dword v78, v[78:79], off
	global_load_dword v80, v[80:81], off
	global_load_dword v82, v[82:83], off
	global_load_dword v84, v[84:85], off
	global_load_dword v86, v[86:87], off
	global_load_dword v88, v[88:89], off
	global_load_dword v90, v[90:91], off
	global_load_dword v92, v[92:93], off
	global_load_dword v94, v[94:95], off
	global_load_dword v96, v[96:97], off
	global_load_dword v98, v[98:99], off
	global_load_dword v100, v[100:101], off
	global_load_dword v102, v[102:103], off
	global_load_dword v104, v[104:105], off
	global_load_dword v106, v[106:107], off
	global_load_dword v108, v[108:109], off
	global_load_dword v110, v[110:111], off
	global_load_dword v112, v[112:113], off
	global_load_dword v114, v[114:115], off
	global_load_dword v116, v[116:117], off
	global_load_dword v118, v[118:119], off
	global_load_dword v120, v[120:121], off
	global_load_dword v122, v[122:123], off
	global_load_dword v124, v[124:125], off
	global_load_dword v126, v[126:127], off
	global_load_dword v128, v[128:129], off
	global_load_dword v136, v[136:137], off
	global_load_dword v138, v[138:139], off
	global_load_dword v140, v[140:141], off
	v_add_u32_e32 v32, 0x400, v171
	v_mov_b32_e32 v162, 0
	s_mov_b32 s3, -4
	v_mov_b32_e32 v145, v172
	v_mov_b32_e32 v163, v162
	v_mov_b32_e32 v148, v162
	v_mov_b32_e32 v149, v162
	v_mov_b32_e32 v150, v162
	v_mov_b32_e32 v151, v162
	v_mov_b32_e32 v152, v162
	v_mov_b32_e32 v153, v162
	v_mov_b32_e32 v154, v162
	v_mov_b32_e32 v155, v162
	v_mov_b32_e32 v156, v162
	v_mov_b32_e32 v157, v162
	v_mov_b32_e32 v158, v162
	v_mov_b32_e32 v159, v162
	v_mov_b32_e32 v160, v162
	v_mov_b32_e32 v161, v162
	s_mov_b64 s[6:7], 0x8000
	s_waitcnt vmcnt(56)
	v_mul_f32_e32 v6, v6, v14
	v_mul_f32_e32 v8, v8, v16
	v_mul_f32_e32 v10, v10, v18
	v_mul_f32_e32 v12, v12, v20
	ds_write2_b32 v171, v6, v8 offset1:32
	ds_write2_b32 v171, v10, v12 offset0:64 offset1:96
	s_waitcnt vmcnt(48)
	v_mul_f32_e32 v22, v22, v30
	v_mul_f32_e32 v24, v24, v34
	v_mul_f32_e32 v26, v26, v36
	v_mul_f32_e32 v28, v28, v38
	ds_write2_b32 v171, v22, v24 offset0:128 offset1:160
	ds_write2_b32 v171, v26, v28 offset0:192 offset1:224
	s_waitcnt vmcnt(40)
	v_mul_f32_e32 v40, v40, v48
	v_mul_f32_e32 v42, v42, v50
	v_mul_f32_e32 v44, v44, v52
	v_mul_f32_e32 v46, v46, v54
	ds_write2_b32 v32, v40, v42 offset1:32
	ds_write2_b32 v32, v44, v46 offset0:64 offset1:96
	s_waitcnt vmcnt(32)
	v_mul_f32_e32 v56, v56, v64
	v_mul_f32_e32 v58, v58, v66
	v_mul_f32_e32 v60, v60, v68
	v_mul_f32_e32 v62, v62, v70
	ds_write2_b32 v32, v56, v58 offset0:128 offset1:160
	ds_write2_b32 v32, v60, v62 offset0:192 offset1:224
	v_add_u32_e32 v32, 0x800, v171
	s_waitcnt vmcnt(24)
	v_mul_f32_e32 v72, v72, v80
	v_mul_f32_e32 v74, v74, v82
	v_mul_f32_e32 v76, v76, v84
	v_mul_f32_e32 v78, v78, v86
	ds_write2_b32 v32, v72, v74 offset1:32
	ds_write2_b32 v32, v76, v78 offset0:64 offset1:96
	s_waitcnt vmcnt(16)
	v_mul_f32_e32 v88, v88, v96
	v_mul_f32_e32 v90, v90, v98
	v_mul_f32_e32 v92, v92, v100
	v_mul_f32_e32 v94, v94, v102
	ds_write2_b32 v32, v88, v90 offset0:128 offset1:160
	ds_write2_b32 v32, v92, v94 offset0:192 offset1:224
	v_add_u32_e32 v32, 0xc00, v171
	s_waitcnt vmcnt(8)
	v_mul_f32_e32 v104, v104, v112
	v_mul_f32_e32 v106, v106, v114
	v_mul_f32_e32 v108, v108, v116
	v_mul_f32_e32 v110, v110, v118
	ds_write2_b32 v32, v104, v106 offset1:32
	ds_write2_b32 v32, v108, v110 offset0:64 offset1:96
	s_waitcnt vmcnt(0)
	v_mul_f32_e32 v120, v120, v128
	v_mul_f32_e32 v122, v122, v136
	v_mul_f32_e32 v124, v124, v138
	v_mul_f32_e32 v126, v126, v140
	ds_write2_b32 v32, v120, v122 offset0:128 offset1:160
	ds_write2_b32 v32, v124, v126 offset0:192 offset1:224
	s_waitcnt lgkmcnt(0)
	s_barrier

; template <int M> DEVI float shx(float v) { return __int_as_float(__builtin_amdgcn_ds_swizzle(__float_as_int(v), (M << 10) | 0x1f)); }
; DEVI void sk_gemm(const float* __restrict__ A, int lda, int K, const float* __restrict__ W, int N, const float* __restrict__ gain,
;                   bool use_rs, float* __restrict__ out, int ldo, int mode, unsigned char* lds, int wv, int bid, int nblk) {
;     ...
;   for (int grp = bid; grp < ngrp; grp += nblk) {
;     const int n = grp * 16 + c16; const int nl = n < N ? n : N - 1;
;     float acc[16];
; #pragma unroll
;     for (int b = 0; b < 16; ++b) acc[b] = 0.f;
; #pragma unroll 1
;     for (int k0 = 0; k0 < K; k0 += 1024) {
;       const int kc = (K - k0) < 1024 ? (K - k0) : 1024;
;       __syncthreads();
;       {
;         const int b = tid >> 5, j = tid & 31; float ss = 0.f;
; #pragma unroll 8
;         for (int k = j; k < kc; k += 32) { const float v = A[(size_t)b * lda + k0 + k]; ss += v * v; As[b * 1024 + k] = v * gain[k0 + k]; }
;         if (use_rs) { ss += shx<16>(ss); ss += shx<8>(ss); ss += shx<4>(ss); ss += shx<2>(ss); ss += shx<1>(ss); if (j == 0) rsS[b] = rsqrtf(ss / (float)K + 1e-6f); }
;       }
;       __syncthreads();
.LBB0_1854:
	v_ashrrev_i32_e32 v145, 31, v144
	s_mov_b64 s[6:7], 0x3ff
	v_cmp_gt_i64_e64 s[6:7], s[6:7], v[144:145]
	s_barrier
	s_nop 0
	v_cndmask_b32_e64 v1, 0, v145, s[6:7]
	v_cndmask_b32_e64 v0, v226, v144, s[6:7]
	v_lshl_add_u64 v[146:147], v[0:1], 2, v[142:143]
	global_load_dword v6, v[6:7], off
	global_load_dword v8, v[8:9], off
	global_load_dword v10, v[10:11], off
	global_load_dword v12, v[12:13], off
	global_load_dword v14, v[14:15], off
	global_load_dword v16, v[16:17], off
	global_load_dword v18, v[18:19], off
	global_load_dword v20, v[20:21], off
	global_load_dword v22, v[22:23], off
	global_load_dword v24, v[24:25], off
	global_load_dword v26, v[26:27], off
	global_load_dword v28, v[28:29], off
	global_load_dword v30, v[30:31], off
	global_load_dword v34, v[34:35], off
	global_load_dword v36, v[36:37], off
	global_load_dword v38, v[38:39], off
	global_load_dword v40, v[40:41], off
	global_load_dword v42, v[42:43], off
	global_load_dword v44, v[44:45], off
	global_load_dword v46, v[46:47], off
	global_load_dword v48, v[48:49], off
	global_load_dword v50, v[50:51], off
	global_load_dword v52, v[52:53], off
	global_load_dword v54, v[54:55], off
	global_load_dword v56, v[56:57], off
	global_load_dword v58, v[58:59], off
	global_load_dword v60, v[60:61], off
	global_load_dword v62, v[62:63], off
	global_load_dword v64, v[64:65], off
	global_load_dword v66, v[66:67], off
	global_load_dword v68, v[68:69], off
	global_load_dword v70, v[70:71], off
	global_load_dword v72, v[72:73], off
	global_load_dword v74, v[74:75], off
	global_load_dword v76, v[76:77], off
	global_load_dword v78, v[78:79], off
	global_load_dword v80, v[80:81], off
	global_load_dword v82, v[82:83], off
	global_load_dword v84, v[84:85], off
	global_load_dword v86, v[86:87], off
	global_load_dword v88, v[88:89], off
	global_load_dword v90, v[90:91], off
	global_load_dword v92, v[92:93], off
	global_load_dword v94, v[94:95], off
	global_load_dword v96, v[96:97], off
	global_load_dword v98, v[98:99], off
	global_load_dword v100, v[100:101], off
	global_load_dword v102, v[102:103], off
	global_load_dword v104, v[104:105], off
	global_load_dword v106, v[106:107], off
	global_load_dword v108, v[108:109], off
	global_load_dword v110, v[110:111], off
	global_load_dword v112, v[112:113], off
	global_load_dword v114, v[114:115], off
	global_load_dword v116, v[116:117], off
	global_load_dword v118, v[118:119], off
	global_load_dword v120, v[120:121], off
	global_load_dword v122, v[122:123], off
	global_load_dword v124, v[124:125], off
	global_load_dword v126, v[126:127], off
	global_load_dword v128, v[128:129], off
	global_load_dword v136, v[136:137], off
	global_load_dword v138, v[138:139], off
	global_load_dword v140, v[140:141], off
	v_add_u32_e32 v32, 0x400, v171
	v_mov_b32_e32 v162, 0
	s_mov_b32 s3, -4
	v_mov_b32_e32 v145, v172
	v_mov_b32_e32 v163, v162
	v_mov_b32_e32 v148, v162
	v_mov_b32_e32 v149, v162
	v_mov_b32_e32 v150, v162
	v_mov_b32_e32 v151, v162
	v_mov_b32_e32 v152, v162
	v_mov_b32_e32 v153, v162
	v_mov_b32_e32 v154, v162
	v_mov_b32_e32 v155, v162
	v_mov_b32_e32 v156, v162
	v_mov_b32_e32 v157, v162
	v_mov_b32_e32 v158, v162
	v_mov_b32_e32 v159, v162
	v_mov_b32_e32 v160, v162
	v_mov_b32_e32 v161, v162
	s_mov_b64 s[8:9], 0x8000
	s_waitcnt vmcnt(56)
	v_mul_f32_e32 v6, v6, v14
	v_mul_f32_e32 v8, v8, v16
	v_mul_f32_e32 v10, v10, v18
	v_mul_f32_e32 v12, v12, v20
	ds_write2_b32 v171, v6, v8 offset1:32
	ds_write2_b32 v171, v10, v12 offset0:64 offset1:96
	s_waitcnt vmcnt(48)
	v_mul_f32_e32 v22, v22, v30
	v_mul_f32_e32 v24, v24, v34
	v_mul_f32_e32 v26, v26, v36
	v_mul_f32_e32 v28, v28, v38
	ds_write2_b32 v171, v22, v24 offset0:128 offset1:160
	ds_write2_b32 v171, v26, v28 offset0:192 offset1:224
	s_waitcnt vmcnt(40)
	v_mul_f32_e32 v40, v40, v48
	v_mul_f32_e32 v42, v42, v50
	v_mul_f32_e32 v44, v44, v52
	v_mul_f32_e32 v46, v46, v54
	ds_write2_b32 v32, v40, v42 offset1:32
	ds_write2_b32 v32, v44, v46 offset0:64 offset1:96
	s_waitcnt vmcnt(32)
	v_mul_f32_e32 v56, v56, v64
	v_mul_f32_e32 v58, v58, v66
	v_mul_f32_e32 v60, v60, v68
	v_mul_f32_e32 v62, v62, v70
	ds_write2_b32 v32, v56, v58 offset0:128 offset1:160
	ds_write2_b32 v32, v60, v62 offset0:192 offset1:224
	v_add_u32_e32 v32, 0x800, v171
	s_waitcnt vmcnt(24)
	v_mul_f32_e32 v72, v72, v80
	v_mul_f32_e32 v74, v74, v82
	v_mul_f32_e32 v76, v76, v84
	v_mul_f32_e32 v78, v78, v86
	ds_write2_b32 v32, v72, v74 offset1:32
	ds_write2_b32 v32, v76, v78 offset0:64 offset1:96
	s_waitcnt vmcnt(16)
	v_mul_f32_e32 v88, v88, v96
	v_mul_f32_e32 v90, v90, v98
	v_mul_f32_e32 v92, v92, v100
	v_mul_f32_e32 v94, v94, v102
	ds_write2_b32 v32, v88, v90 offset0:128 offset1:160
	ds_write2_b32 v32, v92, v94 offset0:192 offset1:224
	v_add_u32_e32 v32, 0xc00, v171
	s_waitcnt vmcnt(8)
	v_mul_f32_e32 v104, v104, v112
	v_mul_f32_e32 v106, v106, v114
	v_mul_f32_e32 v108, v108, v116
	v_mul_f32_e32 v110, v110, v118
	ds_write2_b32 v32, v104, v106 offset1:32
	ds_write2_b32 v32, v108, v110 offset0:64 offset1:96
	s_waitcnt vmcnt(0)
	v_mul_f32_e32 v120, v120, v128
	v_mul_f32_e32 v122, v122, v136
	v_mul_f32_e32 v124, v124, v138
	v_mul_f32_e32 v126, v126, v140
	ds_write2_b32 v32, v120, v122 offset0:128 offset1:160
	ds_write2_b32 v32, v124, v126 offset0:192 offset1:224
	s_waitcnt lgkmcnt(0)
	s_barrier
